# v12 with the GEMM K-loop back edge rotated: counter update and exit test moved in front of the iteration's last barrier
# baseline (speedup 1.0000x reference)
.LBB0_270:
	v_add_u32_e32 v140, 0x10000, v223
	v_add_u32_e32 v156, 0x14000, v223
	s_waitcnt lgkmcnt(0)
	ds_read_b128 v[128:131], v140
	ds_read_b128 v[132:135], v140 offset:1024
	ds_read_b128 v[136:139], v140 offset:2048
	ds_read_b128 v[140:143], v140 offset:3072
	ds_read_b128 v[144:147], v156
	ds_read_b128 v[148:151], v156 offset:1024
	ds_read_b128 v[152:155], v156 offset:2048
	ds_read_b128 v[182:185], v156 offset:3072
	s_add_i32 s44, s3, 0x80
	s_cmp_eq_u32 s100, s43
	s_cselect_b32 s45, s25, s44
	s_cselect_b32 s90, s2, s42
	s_add_i32 s44, s45, 0x80
	s_add_i32 s48, s73, s3
	s_mov_b32 s76, s46
	s_mov_b32 m0, s96
	ds_read_b128 v[186:189], v224
	ds_read_b128 v[190:193], v224 offset:1024
	ds_read_b128 v[232:235], v224 offset:2048
	ds_read_b128 v[236:239], v224 offset:3072
	ds_read_b128 v[240:243], v224 offset:4096
	ds_read_b128 v[244:247], v224 offset:5120
	ds_read_b128 v[248:251], v224 offset:6144
	ds_read_b128 v[202:205], v224 offset:7168
	buffer_load_dwordx4 v217, s[76:79], s48 offen lds
	s_mov_b32 m0, s97
	s_nop 0
	buffer_load_dwordx4 v219, s[76:79], s48 offen lds
	s_waitcnt vmcnt(8)
	s_waitcnt lgkmcnt(0)
	s_barrier
	s_setprio 1
	s_waitcnt lgkmcnt(7)
	v_mfma_f32_16x16x32_bf16 v[124:127], v[128:131], v[186:189], v[124:127]
	v_mfma_f32_16x16x32_bf16 v[120:123], v[136:139], v[186:189], v[120:123]
	s_waitcnt lgkmcnt(5)
	v_mfma_f32_16x16x32_bf16 v[108:111], v[128:131], v[232:235], v[108:111]
	v_mfma_f32_16x16x32_bf16 v[104:107], v[136:139], v[232:235], v[104:107]
	s_waitcnt lgkmcnt(3)
	v_mfma_f32_16x16x32_bf16 v[92:95], v[128:131], v[240:243], v[92:95]
	v_mfma_f32_16x16x32_bf16 v[88:91], v[136:139], v[240:243], v[88:91]
	s_waitcnt lgkmcnt(1)
	v_mfma_f32_16x16x32_bf16 v[76:79], v[128:131], v[248:251], v[76:79]
	v_mfma_f32_16x16x32_bf16 v[72:75], v[136:139], v[248:251], v[72:75]
	v_mfma_f32_16x16x32_bf16 v[124:127], v[132:135], v[190:193], v[124:127]
	v_mfma_f32_16x16x32_bf16 v[120:123], v[140:143], v[190:193], v[120:123]
	v_mfma_f32_16x16x32_bf16 v[108:111], v[132:135], v[236:239], v[108:111]
	v_mfma_f32_16x16x32_bf16 v[104:107], v[140:143], v[236:239], v[104:107]
	v_mfma_f32_16x16x32_bf16 v[92:95], v[132:135], v[244:247], v[92:95]
	v_mfma_f32_16x16x32_bf16 v[88:91], v[140:143], v[244:247], v[88:91]
	s_waitcnt lgkmcnt(0)
	v_mfma_f32_16x16x32_bf16 v[76:79], v[132:135], v[202:205], v[76:79]
	v_mfma_f32_16x16x32_bf16 v[72:75], v[140:143], v[202:205], v[72:75]
	s_setprio 0
	s_setprio 1
	v_mfma_f32_16x16x32_bf16 v[116:119], v[144:147], v[186:189], v[116:119]
	v_mfma_f32_16x16x32_bf16 v[112:115], v[152:155], v[186:189], v[112:115]
	v_mfma_f32_16x16x32_bf16 v[100:103], v[144:147], v[232:235], v[100:103]
	v_mfma_f32_16x16x32_bf16 v[96:99], v[152:155], v[232:235], v[96:99]
	v_mfma_f32_16x16x32_bf16 v[84:87], v[144:147], v[240:243], v[84:87]
	v_mfma_f32_16x16x32_bf16 v[80:83], v[152:155], v[240:243], v[80:83]
	v_mfma_f32_16x16x32_bf16 v[68:71], v[144:147], v[248:251], v[68:71]
	v_mfma_f32_16x16x32_bf16 v[64:67], v[152:155], v[248:251], v[64:67]
	v_mfma_f32_16x16x32_bf16 v[116:119], v[148:151], v[190:193], v[116:119]
	v_mfma_f32_16x16x32_bf16 v[112:115], v[182:185], v[190:193], v[112:115]
	v_mfma_f32_16x16x32_bf16 v[100:103], v[148:151], v[236:239], v[100:103]
	v_mfma_f32_16x16x32_bf16 v[96:99], v[182:185], v[236:239], v[96:99]
	v_mfma_f32_16x16x32_bf16 v[84:87], v[148:151], v[244:247], v[84:87]
	v_mfma_f32_16x16x32_bf16 v[80:83], v[182:185], v[244:247], v[80:83]
	v_mfma_f32_16x16x32_bf16 v[68:71], v[148:151], v[202:205], v[68:71]
	v_mfma_f32_16x16x32_bf16 v[64:67], v[182:185], v[202:205], v[64:67]
	s_setprio 0
	s_barrier
	s_mov_b32 m0, s71
	s_mov_b32 s48, s94
	s_mov_b32 s50, s78
	s_mov_b32 s51, s79
	ds_read_b128 v[186:189], v224 offset:16384
	ds_read_b128 v[190:193], v224 offset:17408
	ds_read_b128 v[202:205], v224 offset:18432
	ds_read_b128 v[232:235], v224 offset:19456
	ds_read_b128 v[236:239], v224 offset:20480
	ds_read_b128 v[240:243], v224 offset:21504
	ds_read_b128 v[244:247], v224 offset:22528
	ds_read_b128 v[248:251], v224 offset:23552
	buffer_load_dwordx4 v218, s[48:51], s90 offen lds
	s_mov_b32 m0, s28
	s_add_i32 s91, s90, s64
	buffer_load_dwordx4 v220, s[48:51], s90 offen lds
	s_mov_b32 m0, s29
	s_nop 0
	buffer_load_dwordx4 v218, s[48:51], s91 offen lds
	s_mov_b32 m0, s26
	s_nop 0
	buffer_load_dwordx4 v220, s[48:51], s91 offen lds
	s_mov_b32 m0, s70
	s_nop 0
	buffer_load_dwordx4 v217, s[76:79], s45 offen lds
	s_mov_b32 m0, s27
	s_nop 0
	buffer_load_dwordx4 v219, s[76:79], s45 offen lds
	s_waitcnt vmcnt(8)
	s_waitcnt lgkmcnt(0)
	s_barrier
	s_setprio 1
	s_waitcnt lgkmcnt(7)
	v_mfma_f32_16x16x32_bf16 v[60:63], v[128:131], v[186:189], v[60:63]
	v_mfma_f32_16x16x32_bf16 v[56:59], v[136:139], v[186:189], v[56:59]
	s_waitcnt lgkmcnt(5)
	v_mfma_f32_16x16x32_bf16 v[44:47], v[128:131], v[202:205], v[44:47]
	v_mfma_f32_16x16x32_bf16 v[40:43], v[136:139], v[202:205], v[40:43]
	s_waitcnt lgkmcnt(3)
	v_mfma_f32_16x16x32_bf16 v[28:31], v[128:131], v[236:239], v[28:31]
	v_mfma_f32_16x16x32_bf16 v[24:27], v[136:139], v[236:239], v[24:27]
	s_waitcnt lgkmcnt(1)
	v_mfma_f32_16x16x32_bf16 v[12:15], v[128:131], v[244:247], v[12:15]
	v_mfma_f32_16x16x32_bf16 v[8:11], v[136:139], v[244:247], v[8:11]
	v_mfma_f32_16x16x32_bf16 v[60:63], v[132:135], v[190:193], v[60:63]
	v_mfma_f32_16x16x32_bf16 v[56:59], v[140:143], v[190:193], v[56:59]
	v_mfma_f32_16x16x32_bf16 v[44:47], v[132:135], v[232:235], v[44:47]
	v_mfma_f32_16x16x32_bf16 v[40:43], v[140:143], v[232:235], v[40:43]
	v_mfma_f32_16x16x32_bf16 v[28:31], v[132:135], v[240:243], v[28:31]
	v_mfma_f32_16x16x32_bf16 v[24:27], v[140:143], v[240:243], v[24:27]
	s_waitcnt lgkmcnt(0)
	v_mfma_f32_16x16x32_bf16 v[12:15], v[132:135], v[248:251], v[12:15]
	v_mfma_f32_16x16x32_bf16 v[8:11], v[140:143], v[248:251], v[8:11]
	s_setprio 0
	s_setprio 1
	v_mfma_f32_16x16x32_bf16 v[52:55], v[144:147], v[186:189], v[52:55]
	v_mfma_f32_16x16x32_bf16 v[48:51], v[152:155], v[186:189], v[48:51]
	v_mfma_f32_16x16x32_bf16 v[36:39], v[144:147], v[202:205], v[36:39]
	v_mfma_f32_16x16x32_bf16 v[32:35], v[152:155], v[202:205], v[32:35]
	v_mfma_f32_16x16x32_bf16 v[20:23], v[144:147], v[236:239], v[20:23]
	v_mfma_f32_16x16x32_bf16 v[16:19], v[152:155], v[236:239], v[16:19]
	v_mfma_f32_16x16x32_bf16 v[4:7], v[144:147], v[244:247], v[4:7]
	v_mfma_f32_16x16x32_bf16 v[0:3], v[152:155], v[244:247], v[0:3]
	v_mfma_f32_16x16x32_bf16 v[52:55], v[148:151], v[190:193], v[52:55]
	v_mfma_f32_16x16x32_bf16 v[48:51], v[182:185], v[190:193], v[48:51]
	v_mfma_f32_16x16x32_bf16 v[36:39], v[148:151], v[232:235], v[36:39]
	v_mfma_f32_16x16x32_bf16 v[32:35], v[182:185], v[232:235], v[32:35]
	v_mfma_f32_16x16x32_bf16 v[20:23], v[148:151], v[240:243], v[20:23]
	v_mfma_f32_16x16x32_bf16 v[16:19], v[182:185], v[240:243], v[16:19]
	v_mfma_f32_16x16x32_bf16 v[4:7], v[148:151], v[248:251], v[4:7]
	v_mfma_f32_16x16x32_bf16 v[0:3], v[182:185], v[248:251], v[0:3]
	s_setprio 0
	s_barrier
	v_add_u32_e32 v140, 0x18000, v223
	v_add_u32_e32 v156, 0x1c000, v223
	ds_read_b128 v[128:131], v140
	ds_read_b128 v[132:135], v140 offset:1024
	ds_read_b128 v[136:139], v140 offset:2048
	ds_read_b128 v[140:143], v140 offset:3072
	ds_read_b128 v[144:147], v156
	ds_read_b128 v[148:151], v156 offset:1024
	ds_read_b128 v[152:155], v156 offset:2048
	ds_read_b128 v[182:185], v156 offset:3072
	s_add_i32 s45, s45, s73
	s_mov_b32 m0, s62
	ds_read_b128 v[186:189], v224 offset:32768
	ds_read_b128 v[190:193], v224 offset:33792
	ds_read_b128 v[202:205], v224 offset:34816
	ds_read_b128 v[232:235], v224 offset:35840
	ds_read_b128 v[236:239], v224 offset:36864
	ds_read_b128 v[240:243], v224 offset:37888
	ds_read_b128 v[244:247], v224 offset:38912
	ds_read_b128 v[248:251], v224 offset:39936
	buffer_load_dwordx4 v217, s[76:79], s45 offen lds
	s_mov_b32 m0, s63
	s_nop 0
	buffer_load_dwordx4 v219, s[76:79], s45 offen lds
	s_waitcnt vmcnt(8)
	s_waitcnt lgkmcnt(0)
	s_barrier
	s_setprio 1
	s_waitcnt lgkmcnt(7)
	v_mfma_f32_16x16x32_bf16 v[124:127], v[128:131], v[186:189], v[124:127]
	v_mfma_f32_16x16x32_bf16 v[120:123], v[136:139], v[186:189], v[120:123]
	s_waitcnt lgkmcnt(5)
	v_mfma_f32_16x16x32_bf16 v[108:111], v[128:131], v[202:205], v[108:111]
	v_mfma_f32_16x16x32_bf16 v[104:107], v[136:139], v[202:205], v[104:107]
	s_waitcnt lgkmcnt(3)
	v_mfma_f32_16x16x32_bf16 v[92:95], v[128:131], v[236:239], v[92:95]
	v_mfma_f32_16x16x32_bf16 v[88:91], v[136:139], v[236:239], v[88:91]
	s_waitcnt lgkmcnt(1)
	v_mfma_f32_16x16x32_bf16 v[76:79], v[128:131], v[244:247], v[76:79]
	v_mfma_f32_16x16x32_bf16 v[72:75], v[136:139], v[244:247], v[72:75]
	v_mfma_f32_16x16x32_bf16 v[124:127], v[132:135], v[190:193], v[124:127]
	v_mfma_f32_16x16x32_bf16 v[120:123], v[140:143], v[190:193], v[120:123]
	v_mfma_f32_16x16x32_bf16 v[108:111], v[132:135], v[232:235], v[108:111]
	v_mfma_f32_16x16x32_bf16 v[104:107], v[140:143], v[232:235], v[104:107]
	v_mfma_f32_16x16x32_bf16 v[92:95], v[132:135], v[240:243], v[92:95]
	v_mfma_f32_16x16x32_bf16 v[88:91], v[140:143], v[240:243], v[88:91]
	s_waitcnt lgkmcnt(0)
	v_mfma_f32_16x16x32_bf16 v[76:79], v[132:135], v[248:251], v[76:79]
	v_mfma_f32_16x16x32_bf16 v[72:75], v[140:143], v[248:251], v[72:75]
	s_setprio 0
	s_setprio 1
	v_mfma_f32_16x16x32_bf16 v[116:119], v[144:147], v[186:189], v[116:119]
	v_mfma_f32_16x16x32_bf16 v[112:115], v[152:155], v[186:189], v[112:115]
	v_mfma_f32_16x16x32_bf16 v[100:103], v[144:147], v[202:205], v[100:103]
	v_mfma_f32_16x16x32_bf16 v[96:99], v[152:155], v[202:205], v[96:99]
	v_mfma_f32_16x16x32_bf16 v[84:87], v[144:147], v[236:239], v[84:87]
	v_mfma_f32_16x16x32_bf16 v[80:83], v[152:155], v[236:239], v[80:83]
	v_mfma_f32_16x16x32_bf16 v[68:71], v[144:147], v[244:247], v[68:71]
	v_mfma_f32_16x16x32_bf16 v[64:67], v[152:155], v[244:247], v[64:67]
	v_mfma_f32_16x16x32_bf16 v[116:119], v[148:151], v[190:193], v[116:119]
	v_mfma_f32_16x16x32_bf16 v[112:115], v[182:185], v[190:193], v[112:115]
	v_mfma_f32_16x16x32_bf16 v[100:103], v[148:151], v[232:235], v[100:103]
	v_mfma_f32_16x16x32_bf16 v[96:99], v[182:185], v[232:235], v[96:99]
	v_mfma_f32_16x16x32_bf16 v[84:87], v[148:151], v[240:243], v[84:87]
	v_mfma_f32_16x16x32_bf16 v[80:83], v[182:185], v[240:243], v[80:83]
	v_mfma_f32_16x16x32_bf16 v[68:71], v[148:151], v[248:251], v[68:71]
	v_mfma_f32_16x16x32_bf16 v[64:67], v[182:185], v[248:251], v[64:67]
	s_setprio 0
	s_barrier
	s_mov_b32 m0, s88
	s_add_i32 s45, s90, 0x80
	ds_read_b128 v[186:189], v224 offset:49152
	ds_read_b128 v[190:193], v224 offset:50176
	ds_read_b128 v[202:205], v224 offset:51200
	ds_read_b128 v[232:235], v224 offset:52224
	ds_read_b128 v[236:239], v224 offset:53248
	ds_read_b128 v[240:243], v224 offset:54272
	ds_read_b128 v[244:247], v224 offset:55296
	ds_read_b128 v[248:251], v224 offset:56320
	buffer_load_dwordx4 v218, s[48:51], s45 offen lds
	s_mov_b32 m0, s82
	s_nop 0
	buffer_load_dwordx4 v220, s[48:51], s45 offen lds
	s_add_i32 s45, s45, s64
	s_mov_b32 m0, s58
	s_nop 0
	buffer_load_dwordx4 v218, s[48:51], s45 offen lds
	s_mov_b32 m0, s59
	s_nop 0
	buffer_load_dwordx4 v220, s[48:51], s45 offen lds
	s_mov_b32 m0, s83
	s_nop 0
	buffer_load_dwordx4 v217, s[76:79], s44 offen lds
	s_mov_b32 m0, s89
	s_nop 0
	buffer_load_dwordx4 v219, s[76:79], s44 offen lds
	s_waitcnt vmcnt(8)
	s_waitcnt lgkmcnt(0)
	s_barrier
	s_setprio 1
	s_waitcnt lgkmcnt(7)
	v_mfma_f32_16x16x32_bf16 v[60:63], v[128:131], v[186:189], v[60:63]
	v_mfma_f32_16x16x32_bf16 v[56:59], v[136:139], v[186:189], v[56:59]
	s_waitcnt lgkmcnt(5)
	v_mfma_f32_16x16x32_bf16 v[44:47], v[128:131], v[202:205], v[44:47]
	v_mfma_f32_16x16x32_bf16 v[40:43], v[136:139], v[202:205], v[40:43]
	s_waitcnt lgkmcnt(3)
	v_mfma_f32_16x16x32_bf16 v[28:31], v[128:131], v[236:239], v[28:31]
	v_mfma_f32_16x16x32_bf16 v[24:27], v[136:139], v[236:239], v[24:27]
	s_waitcnt lgkmcnt(1)
	v_mfma_f32_16x16x32_bf16 v[12:15], v[128:131], v[244:247], v[12:15]
	v_mfma_f32_16x16x32_bf16 v[8:11], v[136:139], v[244:247], v[8:11]
	v_mfma_f32_16x16x32_bf16 v[60:63], v[132:135], v[190:193], v[60:63]
	v_mfma_f32_16x16x32_bf16 v[56:59], v[140:143], v[190:193], v[56:59]
	v_mfma_f32_16x16x32_bf16 v[44:47], v[132:135], v[232:235], v[44:47]
	v_mfma_f32_16x16x32_bf16 v[40:43], v[140:143], v[232:235], v[40:43]
	v_mfma_f32_16x16x32_bf16 v[28:31], v[132:135], v[240:243], v[28:31]
	v_mfma_f32_16x16x32_bf16 v[24:27], v[140:143], v[240:243], v[24:27]
	s_waitcnt lgkmcnt(0)
	v_mfma_f32_16x16x32_bf16 v[12:15], v[132:135], v[248:251], v[12:15]
	v_mfma_f32_16x16x32_bf16 v[8:11], v[140:143], v[248:251], v[8:11]
	s_setprio 0
	s_setprio 1
	v_mfma_f32_16x16x32_bf16 v[52:55], v[144:147], v[186:189], v[52:55]
	v_mfma_f32_16x16x32_bf16 v[48:51], v[152:155], v[186:189], v[48:51]
	v_mfma_f32_16x16x32_bf16 v[36:39], v[144:147], v[202:205], v[36:39]
	v_mfma_f32_16x16x32_bf16 v[32:35], v[152:155], v[202:205], v[32:35]
	v_mfma_f32_16x16x32_bf16 v[20:23], v[144:147], v[236:239], v[20:23]
	v_mfma_f32_16x16x32_bf16 v[16:19], v[152:155], v[236:239], v[16:19]
	v_mfma_f32_16x16x32_bf16 v[4:7], v[144:147], v[244:247], v[4:7]
	v_mfma_f32_16x16x32_bf16 v[0:3], v[152:155], v[244:247], v[0:3]
	v_mfma_f32_16x16x32_bf16 v[52:55], v[148:151], v[190:193], v[52:55]
	v_mfma_f32_16x16x32_bf16 v[48:51], v[182:185], v[190:193], v[48:51]
	v_mfma_f32_16x16x32_bf16 v[36:39], v[148:151], v[232:235], v[36:39]
	v_mfma_f32_16x16x32_bf16 v[32:35], v[182:185], v[232:235], v[32:35]
	v_mfma_f32_16x16x32_bf16 v[20:23], v[148:151], v[240:243], v[20:23]
	v_mfma_f32_16x16x32_bf16 v[16:19], v[182:185], v[240:243], v[16:19]
	v_mfma_f32_16x16x32_bf16 v[4:7], v[148:151], v[248:251], v[4:7]
	v_mfma_f32_16x16x32_bf16 v[0:3], v[182:185], v[248:251], v[0:3]
	s_setprio 0
	s_add_i32 s43, s43, 2
	s_addk_i32 s3, 0x100
	s_addk_i32 s42, 0x100
	s_cmp_ge_i32 s43, s101
	s_barrier
	s_cbranch_scc0 .LBB0_270
	s_and_b64 vcc, exec, s[20:21]
	s_cbranch_vccz .LBB0_273
	s_barrier
